# P3 GEMM units too: first two phases peeled with C=0 chain starts, 130 accumulator zero-inits removed (P1+P3+P4 now)
# speedup vs baseline: 1.0048x; 1.0017x over previous
.LBB0_596:
	s_lshl_b32 s98, s56, 3
	s_add_i32 s98, s98, s2
	s_mul_i32 s98, s98, 3
	v_lshl_add_u32 v164, s56, 8, v172
	s_cmp_eq_u32 s87, 3
	v_mad_i64_i32 v[162:163], s[56:57], v164, s77, v[156:157]
	s_cselect_b64 s[62:63], -1, 0
	s_lshl_b32 s56, s2, 8
	s_ashr_i32 s57, s56, 31
	v_lshl_add_u64 v[2:3], s[56:57], 1, v[162:163]
	s_mov_b32 s7, s3
	v_lshl_add_u64 v[2:3], v[2:3], 0, s[6:7]
	v_lshl_add_u64 v[166:167], v[2:3], 0, v[160:161]
	s_add_i32 s7, s88, -2
	s_add_u32 s89, s60, 0x100
	v_mov_b32_e32 v1, v0
	v_ashrrev_i32_e32 v165, 31, v164
	s_addc_u32 s90, s61, 0
	v_lshl_add_u64 v[168:169], s[58:59], 0, v[152:153]
	v_lshl_add_u64 v[170:171], s[58:59], 0, v[154:155]
	s_mov_b32 s64, 0
	s_mov_b64 s[60:61], 0
	s_xor_b64 s[62:63], s[62:63], -1
	v_add_u32_e32 v1, s79, v173
	s_add_i32 s2, s64, 2
	ds_read_b128 v[132:135], v1
	ds_read_b128 v[136:139], v1 offset:1024
	ds_read_b128 v[140:143], v1 offset:2048
	ds_read_b128 v[178:181], v1 offset:3072
	v_add_u32_e32 v1, s80, v173
	s_add_u32 s65, s58, s60
	ds_read_b128 v[182:185], v1
	ds_read_b128 v[188:191], v1 offset:1024
	ds_read_b128 v[192:195], v1 offset:2048
	ds_read_b128 v[196:199], v1 offset:3072
	s_addc_u32 s66, s59, s61
	s_add_u32 s65, s65, 0x100
	s_addc_u32 s66, s66, 0
	s_add_u32 s75, s89, s60
	s_addc_u32 s91, s90, s61
	s_cmp_eq_u32 s7, s64
	s_cselect_b32 s67, s51, s66
	s_cselect_b32 s66, s50, s65
	s_cselect_b32 s65, s53, s91
	s_cselect_b32 s64, s52, s75
	v_lshl_add_u64 v[2:3], v[168:169], 0, s[60:61]
	s_add_i32 m0, s69, 0xc000
	ds_read_b128 v[200:203], v174
	ds_read_b128 v[204:207], v174 offset:1024
	ds_read_b128 v[208:211], v174 offset:2048
	ds_read_b128 v[212:215], v174 offset:3072
	ds_read_b128 v[216:219], v174 offset:4096
	ds_read_b128 v[220:223], v174 offset:5120
	ds_read_b128 v[224:227], v174 offset:6144
	ds_read_b128 v[228:231], v174 offset:7168
	global_load_lds_dwordx4 v[2:3], off
	v_lshl_add_u64 v[2:3], v[170:171], 0, s[60:61]
	s_add_i32 m0, s69, 0xe000
	s_nop 0
	global_load_lds_dwordx4 v[2:3], off
	s_waitcnt vmcnt(8)
	s_waitcnt lgkmcnt(0)
	s_barrier
	s_setprio 1
	s_waitcnt lgkmcnt(0)
	v_mfma_f32_16x16x32_bf16 v[128:131], v[132:135], v[200:203], 0
	v_mfma_f32_16x16x32_bf16 v[124:127], v[140:143], v[200:203], 0
	v_mfma_f32_16x16x32_bf16 v[112:115], v[132:135], v[208:211], 0
	v_mfma_f32_16x16x32_bf16 v[108:111], v[140:143], v[208:211], 0
	v_mfma_f32_16x16x32_bf16 v[96:99], v[132:135], v[216:219], 0
	v_mfma_f32_16x16x32_bf16 v[92:95], v[140:143], v[216:219], 0
	v_mfma_f32_16x16x32_bf16 v[80:83], v[132:135], v[224:227], 0
	v_mfma_f32_16x16x32_bf16 v[76:79], v[140:143], v[224:227], 0
	v_mfma_f32_16x16x32_bf16 v[128:131], v[136:139], v[204:207], v[128:131]
	v_mfma_f32_16x16x32_bf16 v[124:127], v[178:181], v[204:207], v[124:127]
	v_mfma_f32_16x16x32_bf16 v[112:115], v[136:139], v[212:215], v[112:115]
	v_mfma_f32_16x16x32_bf16 v[108:111], v[178:181], v[212:215], v[108:111]
	v_mfma_f32_16x16x32_bf16 v[96:99], v[136:139], v[220:223], v[96:99]
	v_mfma_f32_16x16x32_bf16 v[92:95], v[178:181], v[220:223], v[92:95]
	v_mfma_f32_16x16x32_bf16 v[80:83], v[136:139], v[228:231], v[80:83]
	v_mfma_f32_16x16x32_bf16 v[76:79], v[178:181], v[228:231], v[76:79]
	s_setprio 0
	s_setprio 1
	v_mfma_f32_16x16x32_bf16 v[120:123], v[182:185], v[200:203], 0
	v_mfma_f32_16x16x32_bf16 v[116:119], v[192:195], v[200:203], 0
	v_mfma_f32_16x16x32_bf16 v[104:107], v[182:185], v[208:211], 0
	v_mfma_f32_16x16x32_bf16 v[100:103], v[192:195], v[208:211], 0
	v_mfma_f32_16x16x32_bf16 v[88:91], v[182:185], v[216:219], 0
	v_mfma_f32_16x16x32_bf16 v[84:87], v[192:195], v[216:219], 0
	v_mfma_f32_16x16x32_bf16 v[72:75], v[182:185], v[224:227], 0
	v_mfma_f32_16x16x32_bf16 v[68:71], v[192:195], v[224:227], 0
	v_mfma_f32_16x16x32_bf16 v[120:123], v[188:191], v[204:207], v[120:123]
	v_mfma_f32_16x16x32_bf16 v[116:119], v[196:199], v[204:207], v[116:119]
	v_mfma_f32_16x16x32_bf16 v[104:107], v[188:191], v[212:215], v[104:107]
	v_mfma_f32_16x16x32_bf16 v[100:103], v[196:199], v[212:215], v[100:103]
	v_mfma_f32_16x16x32_bf16 v[88:91], v[188:191], v[220:223], v[88:91]
	v_mfma_f32_16x16x32_bf16 v[84:87], v[196:199], v[220:223], v[84:87]
	v_mfma_f32_16x16x32_bf16 v[72:75], v[188:191], v[228:231], v[72:75]
	v_mfma_f32_16x16x32_bf16 v[68:71], v[196:199], v[228:231], v[68:71]
	s_setprio 0
	s_barrier
	s_add_i32 s75, s79, s68
	v_lshl_add_u64 v[232:233], s[64:65], 0, v[148:149]
	s_mov_b32 m0, s75
	ds_read_b128 v[200:203], v174 offset:16384
	ds_read_b128 v[204:207], v174 offset:17408
	ds_read_b128 v[208:211], v174 offset:18432
	ds_read_b128 v[212:215], v174 offset:19456
	ds_read_b128 v[216:219], v174 offset:20480
	ds_read_b128 v[220:223], v174 offset:21504
	ds_read_b128 v[224:227], v174 offset:22528
	ds_read_b128 v[228:231], v174 offset:23552
	global_load_lds_dwordx4 v[232:233], off
	s_add_i32 m0, s75, 0x2000
	s_add_u32 s92, s64, 0xa0000
	v_lshl_add_u64 v[234:235], s[64:65], 0, v[144:145]
	s_addc_u32 s93, s65, 0
	s_add_i32 s75, s80, s68
	global_load_lds_dwordx4 v[234:235], off
	v_lshl_add_u64 v[2:3], s[92:93], 0, v[148:149]
	s_mov_b32 m0, s75
	v_lshl_add_u64 v[236:237], s[66:67], 0, v[150:151]
	global_load_lds_dwordx4 v[2:3], off
	v_lshl_add_u64 v[2:3], s[92:93], 0, v[144:145]
	s_add_i32 m0, s75, 0x2000
	v_lshl_add_u64 v[238:239], s[66:67], 0, v[146:147]
	global_load_lds_dwordx4 v[2:3], off
	s_mov_b32 m0, s69
	s_nop 0
	global_load_lds_dwordx4 v[236:237], off
	s_mov_b32 m0, s70
	s_nop 0
	global_load_lds_dwordx4 v[238:239], off
	s_waitcnt vmcnt(8)
	s_waitcnt lgkmcnt(0)
	s_barrier
	s_setprio 1
	s_waitcnt lgkmcnt(0)
	v_mfma_f32_16x16x32_bf16 v[64:67], v[132:135], v[200:203], 0
	v_mfma_f32_16x16x32_bf16 v[60:63], v[140:143], v[200:203], 0
	v_mfma_f32_16x16x32_bf16 v[48:51], v[132:135], v[208:211], 0
	v_mfma_f32_16x16x32_bf16 v[44:47], v[140:143], v[208:211], 0
	v_mfma_f32_16x16x32_bf16 v[32:35], v[132:135], v[216:219], 0
	v_mfma_f32_16x16x32_bf16 v[28:31], v[140:143], v[216:219], 0
	v_mfma_f32_16x16x32_bf16 v[16:19], v[132:135], v[224:227], 0
	v_mfma_f32_16x16x32_bf16 v[12:15], v[140:143], v[224:227], 0
	v_mfma_f32_16x16x32_bf16 v[64:67], v[136:139], v[204:207], v[64:67]
	v_mfma_f32_16x16x32_bf16 v[60:63], v[178:181], v[204:207], v[60:63]
	v_mfma_f32_16x16x32_bf16 v[48:51], v[136:139], v[212:215], v[48:51]
	v_mfma_f32_16x16x32_bf16 v[44:47], v[178:181], v[212:215], v[44:47]
	v_mfma_f32_16x16x32_bf16 v[32:35], v[136:139], v[220:223], v[32:35]
	v_mfma_f32_16x16x32_bf16 v[28:31], v[178:181], v[220:223], v[28:31]
	v_mfma_f32_16x16x32_bf16 v[16:19], v[136:139], v[228:231], v[16:19]
	v_mfma_f32_16x16x32_bf16 v[12:15], v[178:181], v[228:231], v[12:15]
	s_setprio 0
	s_setprio 1
	v_mfma_f32_16x16x32_bf16 v[56:59], v[182:185], v[200:203], 0
	v_mfma_f32_16x16x32_bf16 v[52:55], v[192:195], v[200:203], 0
	v_mfma_f32_16x16x32_bf16 v[40:43], v[182:185], v[208:211], 0
	v_mfma_f32_16x16x32_bf16 v[36:39], v[192:195], v[208:211], 0
	v_mfma_f32_16x16x32_bf16 v[24:27], v[182:185], v[216:219], 0
	v_mfma_f32_16x16x32_bf16 v[20:23], v[192:195], v[216:219], 0
	v_mfma_f32_16x16x32_bf16 v[8:11], v[182:185], v[224:227], 0
	v_mfma_f32_16x16x32_bf16 v[2:5], v[192:195], v[224:227], 0
	v_mfma_f32_16x16x32_bf16 v[56:59], v[188:191], v[204:207], v[56:59]
	v_mfma_f32_16x16x32_bf16 v[52:55], v[196:199], v[204:207], v[52:55]
	v_mfma_f32_16x16x32_bf16 v[40:43], v[188:191], v[212:215], v[40:43]
	v_mfma_f32_16x16x32_bf16 v[36:39], v[196:199], v[212:215], v[36:39]
	v_mfma_f32_16x16x32_bf16 v[24:27], v[188:191], v[220:223], v[24:27]
	v_mfma_f32_16x16x32_bf16 v[20:23], v[196:199], v[220:223], v[20:23]
	v_mfma_f32_16x16x32_bf16 v[8:11], v[188:191], v[228:231], v[8:11]
	v_mfma_f32_16x16x32_bf16 v[2:5], v[196:199], v[228:231], v[2:5]
	s_setprio 0
	s_barrier
	s_branch .Lpeel_mid_p3
	s_nop 0
	s_nop 0
	s_nop 0
	s_nop 0
	s_nop 0
	s_nop 0
	s_nop 0
	s_nop 0
	s_nop 0
	s_nop 0
	s_nop 0
	s_nop 0

.Lpeel_mid_p3:
	s_add_i32 s75, 0, 0x18000
	v_add_u32_e32 v1, s75, v173
	s_add_i32 s91, 0, 0x1c000
	ds_read_b128 v[132:135], v1
	ds_read_b128 v[136:139], v1 offset:1024
	ds_read_b128 v[140:143], v1 offset:2048
	ds_read_b128 v[178:181], v1 offset:3072
	v_add_u32_e32 v1, s91, v173
	ds_read_b128 v[182:185], v1
	ds_read_b128 v[188:191], v1 offset:1024
	ds_read_b128 v[192:195], v1 offset:2048
	ds_read_b128 v[196:199], v1 offset:3072
	s_add_u32 s66, s66, 0xa0000
	s_addc_u32 s67, s67, 0
	s_mov_b32 m0, s71
	v_lshl_add_u64 v[6:7], s[66:67], 0, v[150:151]
	ds_read_b128 v[200:203], v174 offset:32768
	ds_read_b128 v[204:207], v174 offset:33792
	ds_read_b128 v[208:211], v174 offset:34816
	ds_read_b128 v[212:215], v174 offset:35840
	ds_read_b128 v[216:219], v174 offset:36864
	ds_read_b128 v[220:223], v174 offset:37888
	ds_read_b128 v[224:227], v174 offset:38912
	ds_read_b128 v[228:231], v174 offset:39936
	global_load_lds_dwordx4 v[6:7], off
	v_lshl_add_u64 v[6:7], s[66:67], 0, v[146:147]
	s_mov_b32 m0, s72
	s_nop 0
	global_load_lds_dwordx4 v[6:7], off
	s_waitcnt vmcnt(8)
	s_waitcnt lgkmcnt(0)
	s_barrier
	s_setprio 1
	s_waitcnt lgkmcnt(0)
	v_mfma_f32_16x16x32_bf16 v[128:131], v[132:135], v[200:203], v[128:131]
	v_mfma_f32_16x16x32_bf16 v[124:127], v[140:143], v[200:203], v[124:127]
	v_mfma_f32_16x16x32_bf16 v[112:115], v[132:135], v[208:211], v[112:115]
	v_mfma_f32_16x16x32_bf16 v[108:111], v[140:143], v[208:211], v[108:111]
	v_mfma_f32_16x16x32_bf16 v[96:99], v[132:135], v[216:219], v[96:99]
	v_mfma_f32_16x16x32_bf16 v[92:95], v[140:143], v[216:219], v[92:95]
	v_mfma_f32_16x16x32_bf16 v[80:83], v[132:135], v[224:227], v[80:83]
	v_mfma_f32_16x16x32_bf16 v[76:79], v[140:143], v[224:227], v[76:79]
	v_mfma_f32_16x16x32_bf16 v[128:131], v[136:139], v[204:207], v[128:131]
	v_mfma_f32_16x16x32_bf16 v[124:127], v[178:181], v[204:207], v[124:127]
	v_mfma_f32_16x16x32_bf16 v[112:115], v[136:139], v[212:215], v[112:115]
	v_mfma_f32_16x16x32_bf16 v[108:111], v[178:181], v[212:215], v[108:111]
	v_mfma_f32_16x16x32_bf16 v[96:99], v[136:139], v[220:223], v[96:99]
	v_mfma_f32_16x16x32_bf16 v[92:95], v[178:181], v[220:223], v[92:95]
	v_mfma_f32_16x16x32_bf16 v[80:83], v[136:139], v[228:231], v[80:83]
	v_mfma_f32_16x16x32_bf16 v[76:79], v[178:181], v[228:231], v[76:79]
	s_setprio 0
	s_setprio 1
	v_mfma_f32_16x16x32_bf16 v[120:123], v[182:185], v[200:203], v[120:123]
	v_mfma_f32_16x16x32_bf16 v[116:119], v[192:195], v[200:203], v[116:119]
	v_mfma_f32_16x16x32_bf16 v[104:107], v[182:185], v[208:211], v[104:107]
	v_mfma_f32_16x16x32_bf16 v[100:103], v[192:195], v[208:211], v[100:103]
	v_mfma_f32_16x16x32_bf16 v[88:91], v[182:185], v[216:219], v[88:91]
	v_mfma_f32_16x16x32_bf16 v[84:87], v[192:195], v[216:219], v[84:87]
	v_mfma_f32_16x16x32_bf16 v[72:75], v[182:185], v[224:227], v[72:75]
	v_mfma_f32_16x16x32_bf16 v[68:71], v[192:195], v[224:227], v[68:71]
	v_mfma_f32_16x16x32_bf16 v[120:123], v[188:191], v[204:207], v[120:123]
	v_mfma_f32_16x16x32_bf16 v[116:119], v[196:199], v[204:207], v[116:119]
	v_mfma_f32_16x16x32_bf16 v[104:107], v[188:191], v[212:215], v[104:107]
	v_mfma_f32_16x16x32_bf16 v[100:103], v[196:199], v[212:215], v[100:103]
	v_mfma_f32_16x16x32_bf16 v[88:91], v[188:191], v[220:223], v[88:91]
	v_mfma_f32_16x16x32_bf16 v[84:87], v[196:199], v[220:223], v[84:87]
	v_mfma_f32_16x16x32_bf16 v[72:75], v[188:191], v[228:231], v[72:75]
	v_mfma_f32_16x16x32_bf16 v[68:71], v[196:199], v[228:231], v[68:71]
	s_setprio 0
	s_barrier
	s_add_i32 s66, s75, s68
	v_lshl_add_u64 v[6:7], v[232:233], 0, s[14:15]
	s_mov_b32 m0, s66
	ds_read_b128 v[200:203], v174 offset:49152
	ds_read_b128 v[204:207], v174 offset:50176
	ds_read_b128 v[208:211], v174 offset:51200
	ds_read_b128 v[212:215], v174 offset:52224
	ds_read_b128 v[216:219], v174 offset:53248
	ds_read_b128 v[220:223], v174 offset:54272
	ds_read_b128 v[224:227], v174 offset:55296
	ds_read_b128 v[228:231], v174 offset:56320
	global_load_lds_dwordx4 v[6:7], off
	s_add_i32 m0, s66, 0x2000
	s_add_u32 s64, s64, 0xa0080
	v_lshl_add_u64 v[6:7], v[234:235], 0, s[14:15]
	s_addc_u32 s65, s65, 0
	s_add_i32 s66, s91, s68
	global_load_lds_dwordx4 v[6:7], off
	v_lshl_add_u64 v[6:7], s[64:65], 0, v[148:149]
	s_mov_b32 m0, s66
	s_nop 0
	global_load_lds_dwordx4 v[6:7], off
	v_lshl_add_u64 v[6:7], s[64:65], 0, v[144:145]
	s_add_i32 m0, s66, 0x2000
	s_nop 0
	global_load_lds_dwordx4 v[6:7], off
	v_lshl_add_u64 v[6:7], v[236:237], 0, s[14:15]
	s_mov_b32 m0, s73
	s_nop 0
	global_load_lds_dwordx4 v[6:7], off
	v_lshl_add_u64 v[6:7], v[238:239], 0, s[14:15]
	s_mov_b32 m0, s76
	s_nop 0
	global_load_lds_dwordx4 v[6:7], off
	s_waitcnt vmcnt(8)
	s_waitcnt lgkmcnt(0)
	s_barrier
	s_setprio 1
	s_waitcnt lgkmcnt(0)
	v_mfma_f32_16x16x32_bf16 v[64:67], v[132:135], v[200:203], v[64:67]
	v_mfma_f32_16x16x32_bf16 v[60:63], v[140:143], v[200:203], v[60:63]
	v_mfma_f32_16x16x32_bf16 v[48:51], v[132:135], v[208:211], v[48:51]
	v_mfma_f32_16x16x32_bf16 v[44:47], v[140:143], v[208:211], v[44:47]
	v_mfma_f32_16x16x32_bf16 v[32:35], v[132:135], v[216:219], v[32:35]
	v_mfma_f32_16x16x32_bf16 v[28:31], v[140:143], v[216:219], v[28:31]
	v_mfma_f32_16x16x32_bf16 v[16:19], v[132:135], v[224:227], v[16:19]
	v_mfma_f32_16x16x32_bf16 v[12:15], v[140:143], v[224:227], v[12:15]
	v_mfma_f32_16x16x32_bf16 v[64:67], v[136:139], v[204:207], v[64:67]
	v_mfma_f32_16x16x32_bf16 v[60:63], v[178:181], v[204:207], v[60:63]
	v_mfma_f32_16x16x32_bf16 v[48:51], v[136:139], v[212:215], v[48:51]
	v_mfma_f32_16x16x32_bf16 v[44:47], v[178:181], v[212:215], v[44:47]
	v_mfma_f32_16x16x32_bf16 v[32:35], v[136:139], v[220:223], v[32:35]
	v_mfma_f32_16x16x32_bf16 v[28:31], v[178:181], v[220:223], v[28:31]
	v_mfma_f32_16x16x32_bf16 v[16:19], v[136:139], v[228:231], v[16:19]
	v_mfma_f32_16x16x32_bf16 v[12:15], v[178:181], v[228:231], v[12:15]
	s_setprio 0
	s_setprio 1
	v_mfma_f32_16x16x32_bf16 v[56:59], v[182:185], v[200:203], v[56:59]
	v_mfma_f32_16x16x32_bf16 v[52:55], v[192:195], v[200:203], v[52:55]
	v_mfma_f32_16x16x32_bf16 v[40:43], v[182:185], v[208:211], v[40:43]
	v_mfma_f32_16x16x32_bf16 v[36:39], v[192:195], v[208:211], v[36:39]
	v_mfma_f32_16x16x32_bf16 v[24:27], v[182:185], v[216:219], v[24:27]
	v_mfma_f32_16x16x32_bf16 v[20:23], v[192:195], v[216:219], v[20:23]
	v_mfma_f32_16x16x32_bf16 v[6:9], v[182:185], v[224:227], v[8:11]
	v_mfma_f32_16x16x32_bf16 v[2:5], v[192:195], v[224:227], v[2:5]
	v_mfma_f32_16x16x32_bf16 v[56:59], v[188:191], v[204:207], v[56:59]
	v_mfma_f32_16x16x32_bf16 v[52:55], v[196:199], v[204:207], v[52:55]
	v_mfma_f32_16x16x32_bf16 v[40:43], v[188:191], v[212:215], v[40:43]
	v_mfma_f32_16x16x32_bf16 v[36:39], v[196:199], v[212:215], v[36:39]
	v_mfma_f32_16x16x32_bf16 v[24:27], v[188:191], v[220:223], v[24:27]
	v_mfma_f32_16x16x32_bf16 v[20:23], v[196:199], v[220:223], v[20:23]
	v_mfma_f32_16x16x32_bf16 v[8:11], v[188:191], v[228:231], v[6:9]
	v_mfma_f32_16x16x32_bf16 v[4:7], v[196:199], v[228:231], v[2:5]
	s_setprio 0
	s_and_b64 vcc, exec, s[18:19]
	s_cbranch_vccnz .Lhk_skipB
	s_and_b64 vcc, exec, s[62:63]
	s_cbranch_vccnz .Lhk_skipB
	s_cmp_eq_u32 s2, 16
	s_cbranch_scc1 .Lhk_doB
	s_cmp_eq_u32 s2, 24
	s_cbranch_scc0 .Lhk_skipB
